# P4 epilogue x loads without the nt hint (plain global_load_dwordx4); the two halves of each 128B line are fetched by different instructions
# speedup vs baseline: 1.0282x; 1.0016x over previous
.LBB0_614:
	ds_read_b128 v[128:131], v164
	ds_read_b128 v[132:135], v164 offset:1024
	ds_read_b128 v[136:139], v164 offset:2048
	ds_read_b128 v[140:143], v164 offset:3072
	s_add_u32 s26, s24, 0xfffc0080
	s_addc_u32 s27, s25, -1
	s_cmp_eq_u32 s60, 12
	s_cselect_b32 s29, s17, s27
	s_cselect_b32 s28, s23, s26
	s_cselect_b32 s27, s15, s59
	s_cselect_b32 s26, s57, s58
	v_lshl_add_u64 v[196:197], s[24:25], 0, v[150:151]
	s_add_i32 m0, s36, 0xc000
	ds_read_b128 v[158:161], v165
	ds_read_b128 v[168:171], v165 offset:1024
	ds_read_b128 v[172:175], v165 offset:2048
	ds_read_b128 v[176:179], v165 offset:3072
	ds_read_b128 v[180:183], v165 offset:4096
	ds_read_b128 v[184:187], v165 offset:5120
	ds_read_b128 v[188:191], v165 offset:6144
	ds_read_b128 v[192:195], v165 offset:7168
	global_load_lds_dwordx4 v[196:197], off
	v_lshl_add_u64 v[196:197], s[24:25], 0, v[152:153]
	s_add_i32 m0, s36, 0xe000
	s_nop 0
	global_load_lds_dwordx4 v[196:197], off
	s_waitcnt lgkmcnt(8)
	s_barrier
	s_waitcnt lgkmcnt(0)
	s_waitcnt lgkmcnt(0)
	v_mfma_f32_16x16x32_bf16 v[124:127], v[128:131], v[158:161], v[124:127]
	v_mfma_f32_16x16x32_bf16 v[120:123], v[136:139], v[158:161], v[120:123]
	v_mfma_f32_16x16x32_bf16 v[116:119], v[128:131], v[172:175], v[116:119]
	v_mfma_f32_16x16x32_bf16 v[112:115], v[136:139], v[172:175], v[112:115]
	v_mfma_f32_16x16x32_bf16 v[104:107], v[128:131], v[180:183], v[104:107]
	v_mfma_f32_16x16x32_bf16 v[96:99], v[136:139], v[180:183], v[96:99]
	v_mfma_f32_16x16x32_bf16 v[92:95], v[128:131], v[188:191], v[92:95]
	v_mfma_f32_16x16x32_bf16 v[76:79], v[136:139], v[188:191], v[76:79]
	v_mfma_f32_16x16x32_bf16 v[124:127], v[132:135], v[168:171], v[124:127]
	v_mfma_f32_16x16x32_bf16 v[120:123], v[140:143], v[168:171], v[120:123]
	v_mfma_f32_16x16x32_bf16 v[116:119], v[132:135], v[176:179], v[116:119]
	v_mfma_f32_16x16x32_bf16 v[112:115], v[140:143], v[176:179], v[112:115]
	v_mfma_f32_16x16x32_bf16 v[104:107], v[132:135], v[184:187], v[104:107]
	v_mfma_f32_16x16x32_bf16 v[96:99], v[140:143], v[184:187], v[96:99]
	v_mfma_f32_16x16x32_bf16 v[92:95], v[132:135], v[192:195], v[92:95]
	v_mfma_f32_16x16x32_bf16 v[76:79], v[140:143], v[192:195], v[76:79]
	s_barrier
	s_add_i32 s61, s48, s35
	v_lshl_add_u64 v[212:213], s[26:27], 0, v[144:145]
	s_mov_b32 m0, s61
	ds_read_b128 v[196:199], v166
	ds_read_b128 v[200:203], v166 offset:1024
	ds_read_b128 v[204:207], v166 offset:2048
	ds_read_b128 v[208:211], v166 offset:3072
	global_load_lds_dwordx4 v[212:213], off
	v_lshl_add_u64 v[214:215], s[26:27], 0, v[146:147]
	s_add_i32 m0, s61, 0x2000
	s_nop 0
	global_load_lds_dwordx4 v[214:215], off
	s_barrier
	s_waitcnt lgkmcnt(0)
	s_waitcnt lgkmcnt(0)
	v_mfma_f32_16x16x32_bf16 v[108:111], v[196:199], v[158:161], v[108:111]
	v_mfma_f32_16x16x32_bf16 v[100:103], v[204:207], v[158:161], v[100:103]
	v_mfma_f32_16x16x32_bf16 v[88:91], v[196:199], v[172:175], v[88:91]
	v_mfma_f32_16x16x32_bf16 v[84:87], v[204:207], v[172:175], v[84:87]
	v_mfma_f32_16x16x32_bf16 v[80:83], v[196:199], v[180:183], v[80:83]
	v_mfma_f32_16x16x32_bf16 v[72:75], v[204:207], v[180:183], v[72:75]
	v_mfma_f32_16x16x32_bf16 v[68:71], v[196:199], v[188:191], v[68:71]
	v_mfma_f32_16x16x32_bf16 v[64:67], v[204:207], v[188:191], v[64:67]
	v_mfma_f32_16x16x32_bf16 v[108:111], v[200:203], v[168:171], v[108:111]
	v_mfma_f32_16x16x32_bf16 v[100:103], v[208:211], v[168:171], v[100:103]
	v_mfma_f32_16x16x32_bf16 v[88:91], v[200:203], v[176:179], v[88:91]
	v_mfma_f32_16x16x32_bf16 v[84:87], v[208:211], v[176:179], v[84:87]
	v_mfma_f32_16x16x32_bf16 v[80:83], v[200:203], v[184:187], v[80:83]
	v_mfma_f32_16x16x32_bf16 v[72:75], v[208:211], v[184:187], v[72:75]
	v_mfma_f32_16x16x32_bf16 v[68:71], v[200:203], v[192:195], v[68:71]
	v_mfma_f32_16x16x32_bf16 v[64:67], v[208:211], v[192:195], v[64:67]
	s_mov_b32 m0, s36
	v_lshl_add_u64 v[216:217], s[28:29], 0, v[144:145]
	s_barrier
	ds_read_b128 v[158:161], v165 offset:16384
	ds_read_b128 v[168:171], v165 offset:17408
	ds_read_b128 v[172:175], v165 offset:18432
	ds_read_b128 v[176:179], v165 offset:19456
	ds_read_b128 v[180:183], v165 offset:20480
	ds_read_b128 v[184:187], v165 offset:21504
	ds_read_b128 v[188:191], v165 offset:22528
	ds_read_b128 v[192:195], v165 offset:23552
	global_load_lds_dwordx4 v[216:217], off
	v_lshl_add_u64 v[218:219], s[28:29], 0, v[146:147]
	s_mov_b32 m0, s37
	s_nop 0
	global_load_lds_dwordx4 v[218:219], off
	s_barrier
	s_waitcnt lgkmcnt(0)
	s_waitcnt lgkmcnt(0)
	v_mfma_f32_16x16x32_bf16 v[60:63], v[128:131], v[158:161], v[60:63]
	v_mfma_f32_16x16x32_bf16 v[56:59], v[136:139], v[158:161], v[56:59]
	v_mfma_f32_16x16x32_bf16 v[52:55], v[128:131], v[172:175], v[52:55]
	v_mfma_f32_16x16x32_bf16 v[48:51], v[136:139], v[172:175], v[48:51]
	v_mfma_f32_16x16x32_bf16 v[44:47], v[128:131], v[180:183], v[44:47]
	v_mfma_f32_16x16x32_bf16 v[24:27], v[136:139], v[180:183], v[24:27]
	v_mfma_f32_16x16x32_bf16 v[20:23], v[128:131], v[188:191], v[20:23]
	v_mfma_f32_16x16x32_bf16 v[8:11], v[136:139], v[188:191], v[8:11]
	v_mfma_f32_16x16x32_bf16 v[60:63], v[132:135], v[168:171], v[60:63]
	v_mfma_f32_16x16x32_bf16 v[56:59], v[140:143], v[168:171], v[56:59]
	v_mfma_f32_16x16x32_bf16 v[52:55], v[132:135], v[176:179], v[52:55]
	v_mfma_f32_16x16x32_bf16 v[48:51], v[140:143], v[176:179], v[48:51]
	v_mfma_f32_16x16x32_bf16 v[44:47], v[132:135], v[184:187], v[44:47]
	v_mfma_f32_16x16x32_bf16 v[24:27], v[140:143], v[184:187], v[24:27]
	v_mfma_f32_16x16x32_bf16 v[20:23], v[132:135], v[192:195], v[20:23]
	v_mfma_f32_16x16x32_bf16 v[8:11], v[140:143], v[192:195], v[8:11]
	s_barrier
	s_add_u32 s62, s26, 0x40000
	s_addc_u32 s63, s27, 0
	s_add_i32 s61, s49, s35
	v_lshl_add_u64 v[128:129], s[62:63], 0, v[144:145]
	s_mov_b32 m0, s61
	s_nop 0
	global_load_lds_dwordx4 v[128:129], off
	v_lshl_add_u64 v[128:129], s[62:63], 0, v[146:147]
	s_add_i32 m0, s61, 0x2000
	s_nop 0
	global_load_lds_dwordx4 v[128:129], off
	s_waitcnt vmcnt(6)
	s_barrier
	v_mfma_f32_16x16x32_bf16 v[40:43], v[196:199], v[158:161], v[40:43]
	v_mfma_f32_16x16x32_bf16 v[36:39], v[204:207], v[158:161], v[36:39]
	v_mfma_f32_16x16x32_bf16 v[32:35], v[196:199], v[172:175], v[32:35]
	v_mfma_f32_16x16x32_bf16 v[28:31], v[204:207], v[172:175], v[28:31]
	v_mfma_f32_16x16x32_bf16 v[16:19], v[196:199], v[180:183], v[16:19]
	v_mfma_f32_16x16x32_bf16 v[12:15], v[204:207], v[180:183], v[12:15]
	v_mfma_f32_16x16x32_bf16 v[4:7], v[196:199], v[188:191], v[4:7]
	v_mfma_f32_16x16x32_bf16 v[0:3], v[204:207], v[188:191], v[0:3]
	v_mfma_f32_16x16x32_bf16 v[40:43], v[200:203], v[168:171], v[40:43]
	v_mfma_f32_16x16x32_bf16 v[36:39], v[208:211], v[168:171], v[36:39]
	v_mfma_f32_16x16x32_bf16 v[32:35], v[200:203], v[176:179], v[32:35]
	v_mfma_f32_16x16x32_bf16 v[28:31], v[208:211], v[176:179], v[28:31]
	v_mfma_f32_16x16x32_bf16 v[16:19], v[200:203], v[184:187], v[16:19]
	v_mfma_f32_16x16x32_bf16 v[12:15], v[208:211], v[184:187], v[12:15]
	v_mfma_f32_16x16x32_bf16 v[4:7], v[200:203], v[192:195], v[4:7]
	v_mfma_f32_16x16x32_bf16 v[0:3], v[208:211], v[192:195], v[0:3]
	s_add_i32 s61, 0, 0x18000
	v_add_u32_e32 v140, s61, v162
	s_barrier
	ds_read_b128 v[128:131], v140
	ds_read_b128 v[132:135], v140 offset:1024
	ds_read_b128 v[136:139], v140 offset:2048
	ds_read_b128 v[140:143], v140 offset:3072
	s_add_u32 s28, s28, 0x40000
	s_addc_u32 s29, s29, 0
	s_mov_b32 m0, s40
	v_lshl_add_u64 v[196:197], s[28:29], 0, v[144:145]
	ds_read_b128 v[158:161], v165 offset:32768
	ds_read_b128 v[168:171], v165 offset:33792
	ds_read_b128 v[172:175], v165 offset:34816
	ds_read_b128 v[176:179], v165 offset:35840
	ds_read_b128 v[180:183], v165 offset:36864
	ds_read_b128 v[184:187], v165 offset:37888
	ds_read_b128 v[188:191], v165 offset:38912
	ds_read_b128 v[192:195], v165 offset:39936
	global_load_lds_dwordx4 v[196:197], off
	v_lshl_add_u64 v[196:197], s[28:29], 0, v[146:147]
	s_mov_b32 m0, s41
	s_nop 0
	global_load_lds_dwordx4 v[196:197], off
	s_waitcnt lgkmcnt(8)
	s_barrier
	s_waitcnt lgkmcnt(0)
	s_waitcnt lgkmcnt(0)
	v_mfma_f32_16x16x32_bf16 v[124:127], v[128:131], v[158:161], v[124:127]
	v_mfma_f32_16x16x32_bf16 v[120:123], v[136:139], v[158:161], v[120:123]
	v_mfma_f32_16x16x32_bf16 v[116:119], v[128:131], v[172:175], v[116:119]
	v_mfma_f32_16x16x32_bf16 v[112:115], v[136:139], v[172:175], v[112:115]
	v_mfma_f32_16x16x32_bf16 v[104:107], v[128:131], v[180:183], v[104:107]
	v_mfma_f32_16x16x32_bf16 v[96:99], v[136:139], v[180:183], v[96:99]
	v_mfma_f32_16x16x32_bf16 v[92:95], v[128:131], v[188:191], v[92:95]
	v_mfma_f32_16x16x32_bf16 v[76:79], v[136:139], v[188:191], v[76:79]
	v_mfma_f32_16x16x32_bf16 v[124:127], v[132:135], v[168:171], v[124:127]
	v_mfma_f32_16x16x32_bf16 v[120:123], v[140:143], v[168:171], v[120:123]
	v_mfma_f32_16x16x32_bf16 v[116:119], v[132:135], v[176:179], v[116:119]
	v_mfma_f32_16x16x32_bf16 v[112:115], v[140:143], v[176:179], v[112:115]
	v_mfma_f32_16x16x32_bf16 v[104:107], v[132:135], v[184:187], v[104:107]
	v_mfma_f32_16x16x32_bf16 v[96:99], v[140:143], v[184:187], v[96:99]
	v_mfma_f32_16x16x32_bf16 v[92:95], v[132:135], v[192:195], v[92:95]
	v_mfma_f32_16x16x32_bf16 v[76:79], v[140:143], v[192:195], v[76:79]
	s_barrier
	s_add_i32 s28, 0, 0x1c000
	s_add_i32 s29, s61, s35
	v_add_u32_e32 v167, s28, v162
	v_lshl_add_u64 v[212:213], v[212:213], 0, s[4:5]
	s_mov_b32 m0, s29
	ds_read_b128 v[196:199], v167
	ds_read_b128 v[200:203], v167 offset:1024
	ds_read_b128 v[204:207], v167 offset:2048
	ds_read_b128 v[208:211], v167 offset:3072
	global_load_lds_dwordx4 v[212:213], off
	v_lshl_add_u64 v[212:213], v[214:215], 0, s[4:5]
	s_add_i32 m0, s29, 0x2000
	s_nop 0
	global_load_lds_dwordx4 v[212:213], off
	s_barrier
	s_waitcnt lgkmcnt(0)
	s_waitcnt lgkmcnt(0)
	v_mfma_f32_16x16x32_bf16 v[108:111], v[196:199], v[158:161], v[108:111]
	v_mfma_f32_16x16x32_bf16 v[100:103], v[204:207], v[158:161], v[100:103]
	v_mfma_f32_16x16x32_bf16 v[88:91], v[196:199], v[172:175], v[88:91]
	v_mfma_f32_16x16x32_bf16 v[84:87], v[204:207], v[172:175], v[84:87]
	v_mfma_f32_16x16x32_bf16 v[80:83], v[196:199], v[180:183], v[80:83]
	v_mfma_f32_16x16x32_bf16 v[72:75], v[204:207], v[180:183], v[72:75]
	v_mfma_f32_16x16x32_bf16 v[68:71], v[196:199], v[188:191], v[68:71]
	v_mfma_f32_16x16x32_bf16 v[64:67], v[204:207], v[188:191], v[64:67]
	v_mfma_f32_16x16x32_bf16 v[108:111], v[200:203], v[168:171], v[108:111]
	v_mfma_f32_16x16x32_bf16 v[100:103], v[208:211], v[168:171], v[100:103]
	v_mfma_f32_16x16x32_bf16 v[88:91], v[200:203], v[176:179], v[88:91]
	v_mfma_f32_16x16x32_bf16 v[84:87], v[208:211], v[176:179], v[84:87]
	v_mfma_f32_16x16x32_bf16 v[80:83], v[200:203], v[184:187], v[80:83]
	v_mfma_f32_16x16x32_bf16 v[72:75], v[208:211], v[184:187], v[72:75]
	v_mfma_f32_16x16x32_bf16 v[68:71], v[200:203], v[192:195], v[68:71]
	v_mfma_f32_16x16x32_bf16 v[64:67], v[208:211], v[192:195], v[64:67]
	s_mov_b32 m0, s43
	v_lshl_add_u64 v[212:213], v[216:217], 0, s[4:5]
	s_barrier
	ds_read_b128 v[158:161], v165 offset:49152
	ds_read_b128 v[168:171], v165 offset:50176
	ds_read_b128 v[172:175], v165 offset:51200
	ds_read_b128 v[176:179], v165 offset:52224
	ds_read_b128 v[180:183], v165 offset:53248
	ds_read_b128 v[184:187], v165 offset:54272
	ds_read_b128 v[188:191], v165 offset:55296
	ds_read_b128 v[192:195], v165 offset:56320
	global_load_lds_dwordx4 v[212:213], off
	v_lshl_add_u64 v[212:213], v[218:219], 0, s[4:5]
	s_mov_b32 m0, s46
	s_nop 0
	global_load_lds_dwordx4 v[212:213], off
	s_barrier
	s_waitcnt lgkmcnt(0)
	s_waitcnt lgkmcnt(0)
	v_mfma_f32_16x16x32_bf16 v[60:63], v[128:131], v[158:161], v[60:63]
	v_mfma_f32_16x16x32_bf16 v[56:59], v[136:139], v[158:161], v[56:59]
	v_mfma_f32_16x16x32_bf16 v[52:55], v[128:131], v[172:175], v[52:55]
	v_mfma_f32_16x16x32_bf16 v[48:51], v[136:139], v[172:175], v[48:51]
	v_mfma_f32_16x16x32_bf16 v[44:47], v[128:131], v[180:183], v[44:47]
	v_mfma_f32_16x16x32_bf16 v[24:27], v[136:139], v[180:183], v[24:27]
	v_mfma_f32_16x16x32_bf16 v[20:23], v[128:131], v[188:191], v[20:23]
	v_mfma_f32_16x16x32_bf16 v[8:11], v[136:139], v[188:191], v[8:11]
	v_mfma_f32_16x16x32_bf16 v[60:63], v[132:135], v[168:171], v[60:63]
	v_mfma_f32_16x16x32_bf16 v[56:59], v[140:143], v[168:171], v[56:59]
	v_mfma_f32_16x16x32_bf16 v[52:55], v[132:135], v[176:179], v[52:55]
	v_mfma_f32_16x16x32_bf16 v[48:51], v[140:143], v[176:179], v[48:51]
	v_mfma_f32_16x16x32_bf16 v[44:47], v[132:135], v[184:187], v[44:47]
	v_mfma_f32_16x16x32_bf16 v[24:27], v[140:143], v[184:187], v[24:27]
	v_mfma_f32_16x16x32_bf16 v[20:23], v[132:135], v[192:195], v[20:23]
	v_mfma_f32_16x16x32_bf16 v[8:11], v[140:143], v[192:195], v[8:11]
	s_barrier
	s_add_u32 s26, s26, 0x40080
	s_addc_u32 s27, s27, 0
	s_add_i32 s28, s28, s35
	v_lshl_add_u64 v[128:129], s[26:27], 0, v[144:145]
	s_mov_b32 m0, s28
	s_nop 0
	global_load_lds_dwordx4 v[128:129], off
	v_lshl_add_u64 v[128:129], s[26:27], 0, v[146:147]
	s_add_i32 m0, s28, 0x2000
	s_nop 0
	global_load_lds_dwordx4 v[128:129], off
	s_waitcnt vmcnt(6)
	s_barrier
	v_mfma_f32_16x16x32_bf16 v[40:43], v[196:199], v[158:161], v[40:43]
	v_mfma_f32_16x16x32_bf16 v[36:39], v[204:207], v[158:161], v[36:39]
	v_mfma_f32_16x16x32_bf16 v[32:35], v[196:199], v[172:175], v[32:35]
	v_mfma_f32_16x16x32_bf16 v[28:31], v[204:207], v[172:175], v[28:31]
	v_mfma_f32_16x16x32_bf16 v[16:19], v[196:199], v[180:183], v[16:19]
	v_mfma_f32_16x16x32_bf16 v[12:15], v[204:207], v[180:183], v[12:15]
	v_mfma_f32_16x16x32_bf16 v[4:7], v[196:199], v[188:191], v[4:7]
	v_mfma_f32_16x16x32_bf16 v[0:3], v[204:207], v[188:191], v[0:3]
	v_mfma_f32_16x16x32_bf16 v[40:43], v[200:203], v[168:171], v[40:43]
	v_mfma_f32_16x16x32_bf16 v[36:39], v[208:211], v[168:171], v[36:39]
	v_mfma_f32_16x16x32_bf16 v[32:35], v[200:203], v[176:179], v[32:35]
	v_mfma_f32_16x16x32_bf16 v[28:31], v[208:211], v[176:179], v[28:31]
	v_mfma_f32_16x16x32_bf16 v[16:19], v[200:203], v[184:187], v[16:19]
	v_mfma_f32_16x16x32_bf16 v[12:15], v[208:211], v[184:187], v[12:15]
	v_mfma_f32_16x16x32_bf16 v[4:7], v[200:203], v[192:195], v[4:7]
	v_mfma_f32_16x16x32_bf16 v[0:3], v[208:211], v[192:195], v[0:3]
	s_add_i32 s60, s60, 2
	s_add_u32 s24, s24, 0x100
	s_addc_u32 s25, s25, 0
	s_add_u32 s58, s58, 0x100
	s_addc_u32 s59, s59, 0
	s_cmp_gt_u32 s60, 13
	s_barrier
	s_cbranch_scc0 .LBB0_614
	s_lshl_b32 s15, s22, 6
	s_and_b32 s24, s15, 0xfffffc00
	s_ashr_i32 s25, s24, 31
	s_ashr_i32 s23, s22, 31
	v_lshl_or_b32 v128, s56, 8, v163
	s_lshl_b64 s[24:25], s[24:25], 2
	s_add_u32 s24, s38, s24
	v_ashrrev_i32_e32 v129, 31, v128
	s_addc_u32 s25, s39, s25
	v_lshlrev_b64 v[232:233], 2, v[128:129]
	s_lshl_b64 s[22:23], s[22:23], 20
	v_lshl_add_u64 v[158:159], s[52:53], 0, v[232:233]
	v_lshl_add_u64 v[234:235], s[22:23], 0, v[148:149]
	v_lshl_add_u64 v[128:129], s[24:25], 0, v[232:233]
	v_lshl_add_u64 v[160:161], v[158:159], 0, v[234:235]
	v_or_b32_e32 v236, 0x10000, v234
	v_mov_b32_e32 v237, v235
	v_or_b32_e32 v238, 0x20000, v234
	v_mov_b32_e32 v239, v235
	v_or_b32_e32 v240, 0x30000, v234
	v_mov_b32_e32 v241, v235
	global_load_dwordx4 v[168:171], v[160:161], off
	global_load_dwordx4 v[140:143], v[128:129], off
	global_load_dwordx4 v[136:139], v[128:129], off offset:64
	global_load_dwordx4 v[172:175], v[160:161], off offset:64
	global_load_dwordx4 v[176:179], v[160:161], off offset:512
	global_load_dwordx4 v[132:135], v[128:129], off offset:512
	s_nop 0
	global_load_dwordx4 v[128:131], v[128:129], off offset:576
	s_nop 0
	global_load_dwordx4 v[180:183], v[160:161], off offset:576
	v_lshl_add_u64 v[196:197], v[158:159], 0, v[236:237]
	v_lshl_add_u64 v[212:213], v[158:159], 0, v[238:239]
	v_lshl_add_u64 v[158:159], v[158:159], 0, v[240:241]
	global_load_dwordx4 v[184:187], v[196:197], off
	global_load_dwordx4 v[188:191], v[196:197], off offset:64
	global_load_dwordx4 v[192:195], v[196:197], off offset:512
	s_nop 0
	global_load_dwordx4 v[196:199], v[196:197], off offset:576
	s_nop 0
	global_load_dwordx4 v[200:203], v[212:213], off
	global_load_dwordx4 v[204:207], v[212:213], off offset:64
	global_load_dwordx4 v[208:211], v[212:213], off offset:512
	s_nop 0
	global_load_dwordx4 v[212:215], v[212:213], off offset:576
	s_nop 0
	global_load_dwordx4 v[216:219], v[158:159], off
	global_load_dwordx4 v[220:223], v[158:159], off offset:64
	global_load_dwordx4 v[224:227], v[158:159], off offset:512
	global_load_dwordx4 v[228:231], v[158:159], off offset:576
	v_lshl_add_u64 v[158:159], s[30:31], 0, v[234:235]
	v_lshl_add_u64 v[158:159], v[158:159], 0, v[232:233]
	v_lshl_add_u64 v[234:235], s[30:31], 0, v[236:237]
	v_lshl_add_u64 v[236:237], s[30:31], 0, v[238:239]
	v_lshl_add_u64 v[238:239], s[30:31], 0, v[240:241]
	v_lshl_add_u64 v[234:235], v[234:235], 0, v[232:233]
	v_lshl_add_u64 v[236:237], v[236:237], 0, v[232:233]
	v_lshl_add_u64 v[232:233], v[238:239], 0, v[232:233]
	s_mov_b32 s56, s14
	s_mov_b32 s22, s16
	s_mov_b64 s[26:27], s[20:21]
	s_mov_b64 s[24:25], s[18:19]
	s_waitcnt vmcnt(0)
	v_pk_fma_f32 v[126:127], v[126:127], v[142:143], v[170:171]
	v_pk_fma_f32 v[124:125], v[124:125], v[140:141], v[168:169]
	v_pk_fma_f32 v[122:123], v[122:123], v[138:139], v[174:175]
	v_pk_fma_f32 v[120:121], v[120:121], v[136:137], v[172:173]
	v_pk_fma_f32 v[110:111], v[110:111], v[134:135], v[178:179]
	v_pk_fma_f32 v[108:109], v[108:109], v[132:133], v[176:177]
	v_pk_fma_f32 v[102:103], v[102:103], v[130:131], v[182:183]
	v_pk_fma_f32 v[100:101], v[100:101], v[128:129], v[180:181]
	global_store_dwordx4 v[158:159], v[124:127], off
	global_store_dwordx4 v[158:159], v[120:123], off offset:64
	global_store_dwordx4 v[158:159], v[108:111], off offset:512
	global_store_dwordx4 v[158:159], v[100:103], off offset:576
	v_pk_fma_f32 v[90:91], v[90:91], v[134:135], v[194:195]
	v_pk_fma_f32 v[110:111], v[114:115], v[138:139], v[190:191]
	v_pk_fma_f32 v[102:103], v[118:119], v[142:143], v[186:187]
	v_pk_fma_f32 v[100:101], v[116:117], v[140:141], v[184:185]
	v_pk_fma_f32 v[74:75], v[74:75], v[130:131], v[214:215]
	v_pk_fma_f32 v[72:73], v[72:73], v[128:129], v[212:213]
	v_pk_fma_f32 v[66:67], v[66:67], v[130:131], v[230:231]
	v_pk_fma_f32 v[64:65], v[64:65], v[128:129], v[228:229]
	v_pk_fma_f32 v[108:109], v[112:113], v[136:137], v[188:189]
	v_pk_fma_f32 v[88:89], v[88:89], v[132:133], v[192:193]
	v_pk_fma_f32 v[86:87], v[86:87], v[130:131], v[198:199]
	v_pk_fma_f32 v[84:85], v[84:85], v[128:129], v[196:197]
	v_pk_fma_f32 v[106:107], v[106:107], v[142:143], v[202:203]
	v_pk_fma_f32 v[104:105], v[104:105], v[140:141], v[200:201]
	v_pk_fma_f32 v[98:99], v[98:99], v[138:139], v[206:207]
	v_pk_fma_f32 v[96:97], v[96:97], v[136:137], v[204:205]
	v_pk_fma_f32 v[82:83], v[82:83], v[134:135], v[210:211]
	v_pk_fma_f32 v[80:81], v[80:81], v[132:133], v[208:209]
	v_pk_fma_f32 v[94:95], v[94:95], v[142:143], v[218:219]
	v_pk_fma_f32 v[92:93], v[92:93], v[140:141], v[216:217]
	global_store_dwordx4 v[234:235], v[100:103], off
	global_store_dwordx4 v[234:235], v[108:111], off offset:64
	global_store_dwordx4 v[234:235], v[88:91], off offset:512
	global_store_dwordx4 v[234:235], v[84:87], off offset:576
	global_store_dwordx4 v[236:237], v[104:107], off
	global_store_dwordx4 v[236:237], v[96:99], off offset:64
	global_store_dwordx4 v[236:237], v[80:83], off offset:512
	global_store_dwordx4 v[236:237], v[72:75], off offset:576
	global_store_dwordx4 v[232:233], v[92:95], off
	v_pk_fma_f32 v[70:71], v[70:71], v[134:135], v[226:227]
	v_pk_fma_f32 v[74:75], v[78:79], v[138:139], v[222:223]
	v_pk_fma_f32 v[72:73], v[76:77], v[136:137], v[220:221]
	v_pk_fma_f32 v[68:69], v[68:69], v[132:133], v[224:225]
	global_store_dwordx4 v[232:233], v[64:67], off offset:576
	global_store_dwordx4 v[232:233], v[72:75], off offset:64
	global_store_dwordx4 v[232:233], v[68:71], off offset:512
	v_add_co_u32_e32 v64, vcc, s50, v160
	v_lshl_add_u64 v[80:81], v[160:161], 0, s[6:7]
	s_nop 0
	v_addc_co_u32_e32 v65, vcc, 0, v161, vcc
	global_load_dwordx4 v[64:67], v[64:65], off
	s_nop 0
	global_load_dwordx4 v[68:71], v[80:81], off offset:64
	global_load_dwordx4 v[72:75], v[80:81], off offset:512
	global_load_dwordx4 v[76:79], v[80:81], off offset:576
	v_add_co_u32_e32 v80, vcc, s51, v160
	v_lshl_add_u64 v[92:93], v[160:161], 0, s[8:9]
	s_nop 0
	v_addc_co_u32_e32 v81, vcc, 0, v161, vcc
	global_load_dwordx4 v[80:83], v[80:81], off
	s_nop 0
	global_load_dwordx4 v[84:87], v[92:93], off offset:64
	global_load_dwordx4 v[88:91], v[92:93], off offset:512
	s_nop 0
	global_load_dwordx4 v[92:95], v[92:93], off offset:576
	v_add_co_u32_e32 v96, vcc, s54, v160
	v_lshl_add_u64 v[108:109], v[160:161], 0, s[10:11]
	s_nop 0
	v_addc_co_u32_e32 v97, vcc, 0, v161, vcc
	global_load_dwordx4 v[96:99], v[96:97], off
	s_nop 0
	global_load_dwordx4 v[100:103], v[108:109], off offset:64
	global_load_dwordx4 v[104:107], v[108:109], off offset:512
	s_nop 0
	global_load_dwordx4 v[108:111], v[108:109], off offset:576
	v_add_co_u32_e32 v112, vcc, s55, v160
	v_lshl_add_u64 v[124:125], v[160:161], 0, s[12:13]
	s_nop 0
	v_addc_co_u32_e32 v113, vcc, 0, v161, vcc
	global_load_dwordx4 v[112:115], v[112:113], off
	s_nop 0
	global_load_dwordx4 v[116:119], v[124:125], off offset:64
	global_load_dwordx4 v[120:123], v[124:125], off offset:512
	s_nop 0
	global_load_dwordx4 v[124:127], v[124:125], off offset:576
	v_add_co_u32_e32 v168, vcc, s50, v158
	v_lshl_add_u64 v[160:161], v[158:159], 0, s[6:7]
	s_nop 0
	v_addc_co_u32_e32 v169, vcc, 0, v159, vcc
	v_add_co_u32_e32 v172, vcc, s51, v158
	v_lshl_add_u64 v[170:171], v[158:159], 0, s[8:9]
	s_nop 0
	v_addc_co_u32_e32 v173, vcc, 0, v159, vcc
	v_lshl_add_u64 v[174:175], v[158:159], 0, s[10:11]
	s_waitcnt vmcnt(0)
	v_pk_fma_f32 v[62:63], v[62:63], v[142:143], v[66:67]
	v_pk_fma_f32 v[60:61], v[60:61], v[140:141], v[64:65]
	v_pk_fma_f32 v[58:59], v[58:59], v[138:139], v[70:71]
	v_pk_fma_f32 v[56:57], v[56:57], v[136:137], v[68:69]
	v_pk_fma_f32 v[42:43], v[42:43], v[134:135], v[74:75]
	v_pk_fma_f32 v[40:41], v[40:41], v[132:133], v[72:73]
	v_pk_fma_f32 v[38:39], v[38:39], v[130:131], v[78:79]
	v_pk_fma_f32 v[36:37], v[36:37], v[128:129], v[76:77]
	v_pk_fma_f32 v[54:55], v[54:55], v[142:143], v[82:83]
	v_pk_fma_f32 v[28:29], v[28:29], v[128:129], v[92:93]
	v_pk_fma_f32 v[52:53], v[52:53], v[140:141], v[80:81]
	v_pk_fma_f32 v[50:51], v[50:51], v[138:139], v[86:87]
	v_pk_fma_f32 v[48:49], v[48:49], v[136:137], v[84:85]
	v_pk_fma_f32 v[34:35], v[34:35], v[134:135], v[90:91]
	v_pk_fma_f32 v[32:33], v[32:33], v[132:133], v[88:89]
	v_pk_fma_f32 v[30:31], v[30:31], v[130:131], v[94:95]
	global_store_dwordx4 v[168:169], v[60:63], off
	global_store_dwordx4 v[160:161], v[56:59], off offset:64
	global_store_dwordx4 v[160:161], v[40:43], off offset:512
	global_store_dwordx4 v[160:161], v[36:39], off offset:576
	global_store_dwordx4 v[172:173], v[52:55], off
	global_store_dwordx4 v[170:171], v[48:51], off offset:64
	global_store_dwordx4 v[170:171], v[32:35], off offset:512
	global_store_dwordx4 v[170:171], v[28:31], off offset:576
	v_pk_fma_f32 v[18:19], v[18:19], v[134:135], v[106:107]
	v_pk_fma_f32 v[16:17], v[16:17], v[132:133], v[104:105]
	v_add_co_u32_e32 v28, vcc, s54, v158
	global_store_dwordx4 v[174:175], v[16:19], off offset:512
	s_nop 0
	v_addc_co_u32_e32 v29, vcc, 0, v159, vcc
	v_add_co_u32_e32 v18, vcc, s55, v158
	v_pk_fma_f32 v[14:15], v[14:15], v[130:131], v[110:111]
	v_pk_fma_f32 v[12:13], v[12:13], v[128:129], v[108:109]
	v_addc_co_u32_e32 v19, vcc, 0, v159, vcc
	v_pk_fma_f32 v[46:47], v[46:47], v[142:143], v[98:99]
	v_pk_fma_f32 v[44:45], v[44:45], v[140:141], v[96:97]
	v_pk_fma_f32 v[26:27], v[26:27], v[138:139], v[102:103]
	v_pk_fma_f32 v[24:25], v[24:25], v[136:137], v[100:101]
	global_store_dwordx4 v[174:175], v[12:15], off offset:576
	v_lshl_add_u64 v[16:17], v[158:159], 0, s[12:13]
	v_pk_fma_f32 v[10:11], v[10:11], v[138:139], v[118:119]
	v_pk_fma_f32 v[14:15], v[22:23], v[142:143], v[114:115]
	v_pk_fma_f32 v[12:13], v[20:21], v[140:141], v[112:113]
	v_pk_fma_f32 v[8:9], v[8:9], v[136:137], v[116:117]
	v_pk_fma_f32 v[6:7], v[6:7], v[134:135], v[122:123]
	v_pk_fma_f32 v[4:5], v[4:5], v[132:133], v[120:121]
	v_pk_fma_f32 v[2:3], v[2:3], v[130:131], v[126:127]
	v_pk_fma_f32 v[0:1], v[0:1], v[128:129], v[124:125]
	s_and_b64 vcc, exec, s[0:1]
	global_store_dwordx4 v[28:29], v[44:47], off
	global_store_dwordx4 v[174:175], v[24:27], off offset:64
	global_store_dwordx4 v[18:19], v[12:15], off
	global_store_dwordx4 v[16:17], v[8:11], off offset:64
	global_store_dwordx4 v[16:17], v[4:7], off offset:512
	global_store_dwordx4 v[16:17], v[0:3], off offset:576
	s_cbranch_vccz .LBB0_607
	s_waitcnt vmcnt(0)
	s_cmpk_gt_u32 s33, 0xff
	s_cbranch_scc1 .LBB0_618
	s_barrier
